# v31: loop-edge edit - attention tile path decision and fast-path setup moved before the tile barrier; GLA decay-scale addresses formed before barrier B4
# speedup vs baseline: 1.0056x; 1.0056x over previous
; __device__ __forceinline__ void phase_attn(const Frame& F, int l, bool last, int ai, int na) {
;     ...
;         for (int t = 0; t < ntile; ++t) {
;             const int bo = (t & 1) * AT_BUF;
;             __syncthreads();
;             if (t + 1 < ntile) { AT_STORE(AT_BUF - bo); if (t + 2 < ntile) AT_LOAD(t + 2); }
;             const int kpos0 = wlo + t * 64, q0w = qb * 128 + (w & 3) * 32;
;             const bool win = (t < nwin) && !(kpos0 <= q0w + 65 && kpos0 >= q0w - 97);
;             if ((t < nwin) && (kpos0 > q0w + 159 || kpos0 < q0w - 191)) continue;
.LBB0_609:
	s_add_i32 s10, s39, 4
	s_bitcmp1_b32 s10, 0
	s_cselect_b32 s40, 0x8c00, 0
	s_add_i32 s2, s39, 5
	s_add_i32 s41, s27, s38
	s_cmp_ge_i32 s10, s28
	s_cbranch_scc1 .Lattn_fast
	s_cmp_lt_i32 s41, s35
	s_cbranch_scc1 .Lattn_slowtop
	s_cmp_le_i32 s41, s34
	s_cbranch_scc1 .Lattn_fast
.Lattn_slowtop:
	s_waitcnt lgkmcnt(0)
	s_barrier
	s_cmp_ge_i32 s2, s31
	s_cbranch_scc1 .LBB0_612
	s_sub_i32 s2, 0, s40
	v_add_u32_e32 v0, s2, v180
	s_mov_b32 s3, 0x5040100
	s_mov_b32 s11, 0x7060302
	v_add_u32_e32 v3, s2, v181
	s_waitcnt vmcnt(2)
	ds_write_b128 v0, v[148:151] offset:35840
	ds_write_b128 v0, v[144:147] offset:35856
	s_waitcnt vmcnt(0)
	v_perm_b32 v2, v156, v152, s3
	v_perm_b32 v4, v156, v152, s11
	ds_write_b32 v3, v2 offset:53248
	ds_write_b32 v3, v4 offset:53392
	v_perm_b32 v5, v157, v153, s3
	v_perm_b32 v6, v157, v153, s11
	ds_write_b32 v3, v5 offset:53536
	ds_write_b32 v3, v6 offset:53680
	v_perm_b32 v7, v158, v154, s3
	v_perm_b32 v8, v158, v154, s11
	ds_write_b32 v3, v7 offset:53824
	ds_write_b32 v3, v8 offset:53968
	v_perm_b32 v9, v159, v155, s3
	v_perm_b32 v10, v159, v155, s11
	ds_write_b32 v3, v9 offset:54112
	ds_write_b32 v3, v10 offset:54256
	s_add_i32 s2, s39, 6
	s_cmp_ge_i32 s2, s31
	s_cbranch_scc1 .LBB0_612
	s_cmp_lt_i32 s2, s28
	s_cselect_b32 s2, 0, s28
	s_cselect_b32 s3, s29, s26
	s_lshl_b32 s2, s2, 6
	s_sub_i32 s2, s3, s2
	s_add_i32 s11, s2, s38
	v_add_u32_e32 v0, s11, v226
	s_movk_i32 s41, 0x3400
	v_mad_i64_i32 v[2:3], s[2:3], v0, s41, v[174:175]
	v_add_u32_e32 v0, s11, v227
	global_load_dwordx4 v[144:147], v[2:3], off offset:16
	global_load_dwordx4 v[148:151], v[2:3], off
	v_mad_i64_i32 v[2:3], s[2:3], v0, s41, v[176:177]
	v_add_co_u32_e32 v4, vcc, 0x3000, v2
	s_movk_i32 s44, 0x3400
	s_nop 0
	v_addc_co_u32_e32 v5, vcc, 0, v3, vcc
	global_load_dwordx4 v[152:155], v[2:3], off offset:512
	global_load_dwordx4 v[156:159], v[4:5], off offset:1536

; #define LAS __attribute__((address_space(3)))
; __device__ __forceinline__ void phase_attn(const Frame& F, int l, bool last, int ai, int na) {
;     ...
;             const int bo = (t & 1) * AT_BUF;
;             __syncthreads();
;             if (t + 1 < ntile) { AT_STORE(AT_BUF - bo); if (t + 2 < ntile) AT_LOAD(t + 2); }
;             const int kpos0 = wlo + t * 64, q0w = qb * 128 + (w & 3) * 32;
;             const bool win = (t < nwin) && !(kpos0 <= q0w + 65 && kpos0 >= q0w - 97);
;             if ((t < nwin) && (kpos0 > q0w + 159 || kpos0 < q0w - 191)) continue;
;             f32x16 sacc[2];
; #pragma unroll
;             for (int kt = 0; kt < 2; ++kt) {
; #pragma unroll
;                 for (int e = 0; e < 16; ++e) sacc[kt][e] = 0.f;
; #pragma unroll
;                 for (int s = 0; s < 8; ++s) { const f16x8 a = *(const LAS f16x8*)(lds + bo + AT_K + ((kt * 32 + r32) * 136 + s * 16 + hh * 8) * 2);
;                     sacc[kt] = __builtin_amdgcn_mfma_f32_32x32x16_f16(a, qf[s], sacc[kt], 0, 0, 0); } }
.Lattn_fast:
	s_add_i32 s42, s39, 5
	s_cmp_ge_i32 s42, s31
	s_cselect_b32 s42, 1, 0
	s_add_i32 s43, s39, 6
	s_cmp_ge_i32 s43, s31
	s_cselect_b32 s43, 1, 0
	s_add_i32 s2, s40, 0
	s_sub_i32 s41, 0, s40
	s_mov_b32 s3, 0xf149f2ca
	v_add_u32_e32 v14, s2, v189
	s_waitcnt lgkmcnt(0)
	s_barrier
	ds_read_b128 v[2:5], v14
	ds_read_b128 v[6:9], v14 offset:32
	ds_read_b128 v[10:13], v14 offset:64
	ds_read_b128 v[200:203], v14 offset:96
	ds_read_b128 v[242:245], v14 offset:128
	ds_read_b128 v[246:249], v14 offset:160
	s_waitcnt lgkmcnt(5)
	v_mfma_f32_32x32x16_f16 v[96:111], v[2:5], v[112:115], 0
	ds_read_b128 v[2:5], v14 offset:192
	s_waitcnt lgkmcnt(5)
	v_mfma_f32_32x32x16_f16 v[96:111], v[6:9], v[116:119], v[96:111]
	ds_read_b128 v[6:9], v14 offset:224
	s_cmp_eq_u32 s42, 1
	s_cbranch_scc1 .Lf_noS
	s_waitcnt vmcnt(0)
	v_add_u32_e32 v80, s41, v180
	v_add_u32_e32 v81, s41, v181
	s_mov_b32 s10, 0x5040100
	s_mov_b32 s11, 0x7060302
	v_perm_b32 v82, v156, v152, s10
	v_perm_b32 v83, v156, v152, s11
	v_perm_b32 v84, v157, v153, s10
	v_perm_b32 v85, v157, v153, s11
	v_perm_b32 v86, v158, v154, s10
	v_perm_b32 v87, v158, v154, s11
	v_perm_b32 v88, v159, v155, s10
	v_perm_b32 v89, v159, v155, s11

; #define LAS __attribute__((address_space(3)))
; __device__ __forceinline__ void phase_gla(const Frame& F, int l, int gi, int ng, bool last, unsigned* cw) {
;     ...
;             __syncthreads();
; #pragma unroll
;             for (int ks = 0; ks < 4; ++ks) {
;                 const s16x8 a = *(const LAS s16x8*)(lds + GL_AM + ((it * 32 + r32) * 72 + ks * 16 + hh * 8) * 2);
;                 const s16x8 bb = *(const LAS s16x8*)(lds + GL_VT + ((et * 32 + r32) * 72 + ks * 16 + hh * 8) * 2);
;                 oacc = __builtin_amdgcn_mfma_f32_32x32x16_bf16(a, bb, oacc, 0, 0, 0); }
;             { const int cb = chunk_base(s), i0 = it * 32 + 4 * hh; const long rs = dir ? -(long)DM : (long)DM;
;               f16* ob = Oout + (size_t)(cb + (dir ? 63 - i0 : i0)) * DM + h * 256 + sl * 128 + et * 32 + r32;
; #pragma unroll
;               for (int e = 0; e < 16; ++e) ob[((e & 3) + 8 * (e >> 2)) * rs] = (f16)oacc[e]; }
; #pragma unroll
;             for (int q = 0; q < 2; ++q) {
; #pragma unroll
;                 for (int g4 = 0; g4 < 4; ++g4) { const f32x4 ev = *(const LAS f32x4*)(lds + GL_EB + (dt * 32 + g4 * 8 + hh * 4) * 4);
; #pragma unroll
;                     for (int e = 0; e < 4; ++e) Sacc[q][g4 * 4 + e] *= ev[e]; }
; #pragma unroll
;                 for (int ks = 0; ks < 4; ++ks) {
;                     const s16x8 a = *(const LAS s16x8*)(lds + GL_KT + ((dt * 32 + r32) * 72 + ks * 16 + hh * 8) * 2);
.LBB0_662:
	v_add_u32_e32 v176, s24, v121
	v_add_u32_e32 v177, s25, v121
	v_add_u32_e32 v178, s4, v121
	v_add_u32_e32 v179, s5, v121
	s_waitcnt lgkmcnt(0)
	s_barrier
	ds_read_b128 v[184:187], v170
	ds_read_b128 v[214:217], v171
	ds_read_b128 v[188:191], v170 offset:32
	ds_read_b128 v[218:221], v171 offset:32
	ds_read_b128 v[192:195], v170 offset:64
	ds_read_b128 v[222:225], v171 offset:64
	ds_read_b128 v[200:203], v170 offset:96
	ds_read_b128 v[226:229], v171 offset:96
	ds_read_b128 v[230:233], v176
	ds_read_b128 v[242:245], v177
	ds_read_b128 v[246:249], v178
	ds_read_b128 v[62:65], v179
	s_cmp_gt_u32 s14, 3
	s_waitcnt lgkmcnt(10)
	v_mfma_f32_32x32x16_bf16 v[34:49], v[184:187], v[214:217], v[34:49]
	ds_read_b128 v[50:53], v172
	s_waitcnt lgkmcnt(9)
	v_mfma_f32_32x32x16_bf16 v[34:49], v[188:191], v[218:221], v[34:49]
	ds_read_b128 v[54:57], v172 offset:32
	s_waitcnt lgkmcnt(8)
	v_mfma_f32_32x32x16_bf16 v[34:49], v[192:195], v[222:225], v[34:49]
	ds_read_b128 v[58:61], v172 offset:64
	s_waitcnt lgkmcnt(7)
	v_mfma_f32_32x32x16_bf16 v[34:49], v[200:203], v[226:229], v[34:49]
	ds_read_b128 v[180:183], v172 offset:96
	s_mov_b64 s[2:3], -1
	s_cbranch_scc0 .LBB0_664
	s_add_i32 s0, s37, 1
	s_and_b64 s[2:3], s[84:85], exec
	s_cselect_b32 s0, s7, s0
	s_lshl_b32 s0, s0, 6
	s_add_i32 s0, s0, s6
	s_mov_b64 s[2:3], 0
